# plus gdn_pre: forward-substitution LDS reads software-pipelined 2 rows ahead; block off-diagonal stage reads grouped + diagonal block read hoisted
# speedup vs baseline: 1.0149x; 1.0013x over previous
.LBB0_467:
	s_andn2_saveexec_b64 s[2:3], s[38:39]
	s_cbranch_execz .LBB0_469
	v_add_u32_e32 v16, v133, v134
	v_add_u32_e32 v14, v72, v134
	v_add_u32_e32 v159, v72, v135
	ds_write_b32 v16, v92
	ds_read_b32 v216, v14 offset:35088
	ds_read_b64 v[232:233], v14 offset:35360
	s_waitcnt lgkmcnt(1)
	v_fma_f32 v17, -v92, v216, v93
	ds_write_b32 v16, v17 offset:272
	ds_read_b96 v[200:202], v14 offset:35632
	s_waitcnt lgkmcnt(2)
	v_fma_f32 v2, -v92, v232, v94
	v_fma_f32 v59, -v17, v233, v2
	ds_write_b32 v16, v59 offset:544
	ds_read_b128 v[216:219], v14 offset:35904
	s_waitcnt lgkmcnt(2)
	v_fma_f32 v2, -v92, v200, v95
	v_fma_f32 v2, -v17, v201, v2
	v_fma_f32 v148, -v59, v202, v2
	ds_write_b32 v16, v148 offset:816
	ds_read_b128 v[232:235], v14 offset:36176
	ds_read_b32 v236, v14 offset:36192
	s_waitcnt lgkmcnt(3)
	v_fma_f32 v2, -v92, v216, v96
	v_fma_f32 v2, -v17, v217, v2
	v_fma_f32 v2, -v59, v218, v2
	v_fma_f32 v149, -v148, v219, v2
	ds_write_b32 v16, v149 offset:1088
	ds_read_b128 v[200:203], v14 offset:36448
	ds_read_b64 v[204:205], v14 offset:36464
	s_waitcnt lgkmcnt(4)
	v_fma_f32 v2, -v92, v232, v97
	v_fma_f32 v2, -v17, v233, v2
	v_fma_f32 v2, -v59, v234, v2
	v_fma_f32 v2, -v148, v235, v2
	s_waitcnt lgkmcnt(3)
	v_fma_f32 v150, -v149, v236, v2
	ds_write_b32 v16, v150 offset:1360
	ds_read_b128 v[216:219], v14 offset:36720
	ds_read_b96 v[220:222], v14 offset:36736
	s_waitcnt lgkmcnt(4)
	v_fma_f32 v2, -v92, v200, v98
	v_fma_f32 v2, -v17, v201, v2
	v_fma_f32 v2, -v59, v202, v2
	v_fma_f32 v2, -v148, v203, v2
	s_waitcnt lgkmcnt(3)
	v_fma_f32 v2, -v149, v204, v2
	v_fma_f32 v151, -v150, v205, v2
	ds_write_b32 v16, v151 offset:1632
	ds_read_b128 v[232:235], v14 offset:36992
	ds_read_b128 v[236:239], v14 offset:37008
	s_waitcnt lgkmcnt(4)
	v_fma_f32 v2, -v92, v216, v99
	v_fma_f32 v2, -v17, v217, v2
	v_fma_f32 v2, -v59, v218, v2
	v_fma_f32 v2, -v148, v219, v2
	s_waitcnt lgkmcnt(3)
	v_fma_f32 v2, -v149, v220, v2
	v_fma_f32 v2, -v150, v221, v2
	v_fma_f32 v152, -v151, v222, v2
	ds_write_b32 v16, v152 offset:1904
	ds_read_b128 v[200:203], v14 offset:37264
	ds_read_b128 v[204:207], v14 offset:37280
	ds_read_b32 v208, v14 offset:37296
	s_waitcnt lgkmcnt(5)
	v_fma_f32 v2, -v92, v232, v100
	v_fma_f32 v2, -v17, v233, v2
	v_fma_f32 v2, -v59, v234, v2
	v_fma_f32 v2, -v148, v235, v2
	s_waitcnt lgkmcnt(4)
	v_fma_f32 v2, -v149, v236, v2
	v_fma_f32 v2, -v150, v237, v2
	v_fma_f32 v2, -v151, v238, v2
	v_fma_f32 v153, -v152, v239, v2
	ds_write_b32 v16, v153 offset:2176
	ds_read_b128 v[216:219], v14 offset:37536
	ds_read_b128 v[220:223], v14 offset:37552
	ds_read_b64 v[224:225], v14 offset:37568
	s_waitcnt lgkmcnt(6)
	v_fma_f32 v2, -v92, v200, v101
	v_fma_f32 v2, -v17, v201, v2
	v_fma_f32 v2, -v59, v202, v2
	v_fma_f32 v2, -v148, v203, v2
	s_waitcnt lgkmcnt(5)
	v_fma_f32 v2, -v149, v204, v2
	v_fma_f32 v2, -v150, v205, v2
	v_fma_f32 v2, -v151, v206, v2
	v_fma_f32 v2, -v152, v207, v2
	s_waitcnt lgkmcnt(4)
	v_fma_f32 v154, -v153, v208, v2
	ds_write_b32 v16, v154 offset:2448
	ds_read_b128 v[232:235], v14 offset:37808
	ds_read_b128 v[236:239], v14 offset:37824
	ds_read_b96 v[240:242], v14 offset:37840
	s_waitcnt lgkmcnt(6)
	v_fma_f32 v2, -v92, v216, v102
	v_fma_f32 v2, -v17, v217, v2
	v_fma_f32 v2, -v59, v218, v2
	v_fma_f32 v2, -v148, v219, v2
	s_waitcnt lgkmcnt(5)
	v_fma_f32 v2, -v149, v220, v2
	v_fma_f32 v2, -v150, v221, v2
	v_fma_f32 v2, -v151, v222, v2
	v_fma_f32 v2, -v152, v223, v2
	s_waitcnt lgkmcnt(4)
	v_fma_f32 v2, -v153, v224, v2
	v_fma_f32 v155, -v154, v225, v2
	ds_write_b32 v16, v155 offset:2720
	ds_read_b128 v[200:203], v14 offset:38080
	ds_read_b128 v[204:207], v14 offset:38096
	ds_read_b128 v[208:211], v14 offset:38112
	s_waitcnt lgkmcnt(6)
	v_fma_f32 v2, -v92, v232, v103
	v_fma_f32 v2, -v17, v233, v2
	v_fma_f32 v2, -v59, v234, v2
	v_fma_f32 v2, -v148, v235, v2
	s_waitcnt lgkmcnt(5)
	v_fma_f32 v2, -v149, v236, v2
	v_fma_f32 v2, -v150, v237, v2
	v_fma_f32 v2, -v151, v238, v2
	v_fma_f32 v2, -v152, v239, v2
	s_waitcnt lgkmcnt(4)
	v_fma_f32 v2, -v153, v240, v2
	v_fma_f32 v2, -v154, v241, v2
	v_fma_f32 v156, -v155, v242, v2
	ds_write_b32 v16, v156 offset:2992
	ds_read_b128 v[216:219], v14 offset:38352
	ds_read_b128 v[220:223], v14 offset:38368
	ds_read_b128 v[224:227], v14 offset:38384
	ds_read_b32 v228, v14 offset:38400
	s_waitcnt lgkmcnt(7)
	v_fma_f32 v2, -v92, v200, v104
	v_fma_f32 v2, -v17, v201, v2
	v_fma_f32 v2, -v59, v202, v2
	v_fma_f32 v2, -v148, v203, v2
	s_waitcnt lgkmcnt(6)
	v_fma_f32 v2, -v149, v204, v2
	v_fma_f32 v2, -v150, v205, v2
	v_fma_f32 v2, -v151, v206, v2
	v_fma_f32 v2, -v152, v207, v2
	s_waitcnt lgkmcnt(5)
	v_fma_f32 v2, -v153, v208, v2
	v_fma_f32 v2, -v154, v209, v2
	v_fma_f32 v2, -v155, v210, v2
	v_fma_f32 v157, -v156, v211, v2
	ds_write_b32 v16, v157 offset:3264
	ds_read_b128 v[232:235], v14 offset:38624
	ds_read_b128 v[236:239], v14 offset:38640
	ds_read_b128 v[240:243], v14 offset:38656
	ds_read_b64 v[244:245], v14 offset:38672
	s_waitcnt lgkmcnt(8)
	v_fma_f32 v2, -v92, v216, v105
	v_fma_f32 v2, -v17, v217, v2
	v_fma_f32 v2, -v59, v218, v2
	v_fma_f32 v2, -v148, v219, v2
	s_waitcnt lgkmcnt(7)
	v_fma_f32 v2, -v149, v220, v2
	v_fma_f32 v2, -v150, v221, v2
	v_fma_f32 v2, -v151, v222, v2
	v_fma_f32 v2, -v152, v223, v2
	s_waitcnt lgkmcnt(6)
	v_fma_f32 v2, -v153, v224, v2
	v_fma_f32 v2, -v154, v225, v2
	v_fma_f32 v2, -v155, v226, v2
	v_fma_f32 v2, -v156, v227, v2
	s_waitcnt lgkmcnt(5)
	v_fma_f32 v158, -v157, v228, v2
	ds_write_b32 v16, v158 offset:3536
	ds_read_b128 v[200:203], v159 offset:34816
	ds_read_b128 v[204:207], v159 offset:34832
	ds_read_b128 v[208:211], v159 offset:34848
	ds_read_b96 v[212:214], v159 offset:34864
	s_waitcnt lgkmcnt(8)
	v_fma_f32 v2, -v92, v232, v106
	v_fma_f32 v2, -v17, v233, v2
	v_fma_f32 v2, -v59, v234, v2
	v_fma_f32 v2, -v148, v235, v2
	s_waitcnt lgkmcnt(7)
	v_fma_f32 v2, -v149, v236, v2
	v_fma_f32 v2, -v150, v237, v2
	v_fma_f32 v2, -v151, v238, v2
	v_fma_f32 v2, -v152, v239, v2
	s_waitcnt lgkmcnt(6)
	v_fma_f32 v2, -v153, v240, v2
	v_fma_f32 v2, -v154, v241, v2
	v_fma_f32 v2, -v155, v242, v2
	v_fma_f32 v2, -v156, v243, v2
	s_waitcnt lgkmcnt(5)
	v_fma_f32 v2, -v157, v244, v2
	v_fma_f32 v160, -v158, v245, v2
	ds_write_b32 v16, v160 offset:3808
	s_waitcnt lgkmcnt(4)
	v_fma_f32 v2, -v92, v200, v107
	v_fma_f32 v2, -v17, v201, v2
	v_fma_f32 v2, -v59, v202, v2
	v_fma_f32 v2, -v148, v203, v2
	s_waitcnt lgkmcnt(3)
	v_fma_f32 v2, -v149, v204, v2
	v_fma_f32 v2, -v150, v205, v2
	v_fma_f32 v2, -v151, v206, v2
	v_fma_f32 v2, -v152, v207, v2
	s_waitcnt lgkmcnt(2)
	v_fma_f32 v2, -v153, v208, v2
	v_fma_f32 v2, -v154, v209, v2
	v_fma_f32 v2, -v155, v210, v2
	v_fma_f32 v2, -v156, v211, v2
	s_waitcnt lgkmcnt(1)
	v_fma_f32 v2, -v157, v212, v2
	v_fma_f32 v2, -v158, v213, v2
	v_fma_f32 v2, -v160, v214, v2
	v_add_u32_e32 v3, v133, v135
	ds_write_b32 v3, v2

.LBB0_471:
	v_cmp_lt_i32_e32 vcc, s44, v73
	s_and_saveexec_b64 s[2:3], vcc
	s_cbranch_execz .LBB0_470
	v_mov_b32_e32 v2, 0
	v_add_u32_e32 v7, s44, v68
	s_mov_b64 s[38:39], 0
	v_mov_b32_e32 v8, v144
	v_mov_b32_e32 v9, v6
	v_mov_b32_e32 v10, v68
	v_mov_b32_e32 v3, v2
	v_mov_b32_e32 v4, v2
	v_mov_b32_e32 v5, v2
	v_lshlrev_b32_e32 v208, 4, v7
	v_or_b32_e32 v209, v208, v71
	v_or_b32_e32 v208, v208, v74
	v_mul_lo_u32 v209, v209, s79
	v_lshlrev_b32_e32 v208, 2, v208
	v_add3_u32 v209, s77, v208, v209
	ds_read_b128 v[204:207], v209
.LBB0_473:
	v_add_u32_e32 v11, 0, v9
	ds_read_b128 v[12:15], v11
	v_add_u32_e32 v11, 0, v8
	v_add_u32_e32 v16, 0x1e830, v11
	ds_read_b32 v16, v16
	v_add_u32_e32 v197, 0x1e940, v11
	ds_read_b32 v197, v197
	v_add_u32_e32 v198, 0x1ea50, v11
	ds_read_b32 v198, v198
	v_add_u32_e32 v199, 0x1eb60, v11
	ds_read_b32 v199, v199
	v_add_u32_e32 v10, 1, v10
	v_cmp_ge_i32_e32 vcc, v10, v7
	v_add_u32_e32 v9, 64, v9
	v_add_u32_e32 v8, 0x1100, v8
	s_or_b64 s[38:39], vcc, s[38:39]
	s_waitcnt lgkmcnt(3)
	v_mfma_f32_16x16x4_f32 v[2:5], v12, v16, v[2:5]
	s_waitcnt lgkmcnt(2)
	v_mfma_f32_16x16x4_f32 v[2:5], v13, v197, v[2:5]
	s_waitcnt lgkmcnt(1)
	v_mfma_f32_16x16x4_f32 v[2:5], v14, v198, v[2:5]
	s_waitcnt lgkmcnt(0)
	v_mfma_f32_16x16x4_f32 v[2:5], v15, v199, v[2:5]
	s_andn2_b64 exec, exec, s[38:39]
	s_cbranch_execnz .LBB0_473
	s_or_b64 exec, exec, s[38:39]
	v_lshlrev_b32_e32 v7, 4, v7
	v_or_b32_e32 v8, v7, v71
	v_or_b32_e32 v7, v7, v74
	v_mul_lo_u32 v8, v8, s79
	v_lshlrev_b32_e32 v9, 2, v7
	s_nop 1
	ds_write2_b32 v75, v2, v3 offset1:16
	ds_write2_b32 v75, v4, v5 offset0:32 offset1:48
	v_add3_u32 v8, s77, v9, v8
	s_waitcnt lgkmcnt(2)
	v_mfma_f32_16x16x4_f32 v[12:15], v204, v2, 0
	v_mfma_f32_16x16x4_f32 v[12:15], v205, v3, v[12:15]
	v_mad_u64_u32 v[8:9], s[38:39], v7, s79, v[54:55]
	v_mfma_f32_16x16x4_f32 v[12:15], v206, v4, v[12:15]
	v_mfma_f32_16x16x4_f32 v[2:5], v207, v5, v[12:15]
	s_nop 9
	v_xor_b32_e32 v2, 0x80000000, v2
	v_xor_b32_e32 v3, 0x80000000, v3
	v_xor_b32_e32 v4, 0x80000000, v4
	v_xor_b32_e32 v5, 0x80000000, v5
	ds_write2_b32 v8, v2, v3 offset1:68
	ds_write2_b32 v8, v4, v5 offset0:136 offset1:204
	s_branch .LBB0_470
